# attention phase: the 9 table loads per thread issued together with one wait (was load, wait, scale, LDS store nine times)
# speedup vs baseline: 1.0051x; 1.0025x over previous
.LBB0_1150:
	s_or_b64 exec, exec, s[0:1]
	v_readlane_b32 s0, v254, 19
	v_lshlrev_b32_e32 v2, 2, v0
	v_mov_b32_e32 v3, 0
	v_readlane_b32 s1, v254, 20
	v_readlane_b32 s2, v254, 21
	v_readlane_b32 s3, v254, 22
	v_readlane_b32 s4, v254, 23
	v_readlane_b32 s5, v254, 24
	v_readlane_b32 s6, v254, 25
	v_readlane_b32 s7, v254, 26
	v_readlane_b32 s8, v254, 27
	v_readlane_b32 s14, v254, 33
	v_readlane_b32 s15, v254, 34
	s_mov_b64 s[0:1], 0
	s_mov_b32 s4, 0xff01
	v_lshl_add_u64 v[2:3], s[14:15], 0, v[2:3]
	s_movk_i32 s5, 0x101
	s_movk_i32 s6, 0x410
	s_add_i32 s7, 0, 0x18000
	s_mov_b64 s[2:3], 0x800
	s_movk_i32 s8, 0xe0f
	v_mov_b32_e32 v4, v0
	v_readlane_b32 s9, v254, 28
	v_readlane_b32 s10, v254, 29
	v_readlane_b32 s11, v254, 30
	v_readlane_b32 s12, v254, 31
	v_readlane_b32 s13, v254, 32
	global_load_dword v10, v[2:3], off
	v_lshl_add_u64 v[2:3], v[2:3], 0, s[2:3]
	global_load_dword v11, v[2:3], off
	v_lshl_add_u64 v[2:3], v[2:3], 0, s[2:3]
	global_load_dword v12, v[2:3], off
	v_lshl_add_u64 v[2:3], v[2:3], 0, s[2:3]
	global_load_dword v13, v[2:3], off
	v_lshl_add_u64 v[2:3], v[2:3], 0, s[2:3]
	global_load_dword v14, v[2:3], off
	v_lshl_add_u64 v[2:3], v[2:3], 0, s[2:3]
	global_load_dword v15, v[2:3], off
	v_lshl_add_u64 v[2:3], v[2:3], 0, s[2:3]
	global_load_dword v16, v[2:3], off
	v_lshl_add_u64 v[2:3], v[2:3], 0, s[2:3]
	global_load_dword v17, v[2:3], off
	v_lshl_add_u64 v[2:3], v[2:3], 0, s[2:3]
	v_cmp_gt_u32_e32 vcc, 16, v0
	s_and_saveexec_b64 s[0:1], vcc
	global_load_dword v18, v[2:3], off
	s_mov_b64 exec, s[0:1]
	s_waitcnt vmcnt(0)
	v_mov_b32_e32 v4, v0
	v_mul_u32_u24_sdwa v6, v4, s4 dst_sel:DWORD dst_unused:UNUSED_PAD src0_sel:WORD_0 src1_sel:DWORD
	v_mul_lo_u16_sdwa v8, v6, s5 dst_sel:DWORD dst_unused:UNUSED_PAD src0_sel:BYTE_3 src1_sel:DWORD
	v_sub_u16_e32 v8, v4, v8
	v_mul_u32_u24_sdwa v6, v6, s6 dst_sel:DWORD dst_unused:UNUSED_PAD src0_sel:BYTE_3 src1_sel:DWORD
	v_lshlrev_b32_e32 v7, 2, v8
	v_add3_u32 v6, s7, v6, v7
	v_mul_f32_e32 v5, 0x3fb8aa3b, v10
	ds_write_b32 v6, v5
	v_add_u32_e32 v4, 0x200, v0
	v_mul_u32_u24_sdwa v6, v4, s4 dst_sel:DWORD dst_unused:UNUSED_PAD src0_sel:WORD_0 src1_sel:DWORD
	v_mul_lo_u16_sdwa v8, v6, s5 dst_sel:DWORD dst_unused:UNUSED_PAD src0_sel:BYTE_3 src1_sel:DWORD
	v_sub_u16_e32 v8, v4, v8
	v_mul_u32_u24_sdwa v6, v6, s6 dst_sel:DWORD dst_unused:UNUSED_PAD src0_sel:BYTE_3 src1_sel:DWORD
	v_lshlrev_b32_e32 v7, 2, v8
	v_add3_u32 v6, s7, v6, v7
	v_mul_f32_e32 v5, 0x3fb8aa3b, v11
	ds_write_b32 v6, v5
	v_add_u32_e32 v4, 0x400, v0
	v_mul_u32_u24_sdwa v6, v4, s4 dst_sel:DWORD dst_unused:UNUSED_PAD src0_sel:WORD_0 src1_sel:DWORD
	v_mul_lo_u16_sdwa v8, v6, s5 dst_sel:DWORD dst_unused:UNUSED_PAD src0_sel:BYTE_3 src1_sel:DWORD
	v_sub_u16_e32 v8, v4, v8
	v_mul_u32_u24_sdwa v6, v6, s6 dst_sel:DWORD dst_unused:UNUSED_PAD src0_sel:BYTE_3 src1_sel:DWORD
	v_lshlrev_b32_e32 v7, 2, v8
	v_add3_u32 v6, s7, v6, v7
	v_mul_f32_e32 v5, 0x3fb8aa3b, v12
	ds_write_b32 v6, v5
	v_add_u32_e32 v4, 0x600, v0
	v_mul_u32_u24_sdwa v6, v4, s4 dst_sel:DWORD dst_unused:UNUSED_PAD src0_sel:WORD_0 src1_sel:DWORD
	v_mul_lo_u16_sdwa v8, v6, s5 dst_sel:DWORD dst_unused:UNUSED_PAD src0_sel:BYTE_3 src1_sel:DWORD
	v_sub_u16_e32 v8, v4, v8
	v_mul_u32_u24_sdwa v6, v6, s6 dst_sel:DWORD dst_unused:UNUSED_PAD src0_sel:BYTE_3 src1_sel:DWORD
	v_lshlrev_b32_e32 v7, 2, v8
	v_add3_u32 v6, s7, v6, v7
	v_mul_f32_e32 v5, 0x3fb8aa3b, v13
	ds_write_b32 v6, v5
	v_add_u32_e32 v4, 0x800, v0
	v_mul_u32_u24_sdwa v6, v4, s4 dst_sel:DWORD dst_unused:UNUSED_PAD src0_sel:WORD_0 src1_sel:DWORD
	v_mul_lo_u16_sdwa v8, v6, s5 dst_sel:DWORD dst_unused:UNUSED_PAD src0_sel:BYTE_3 src1_sel:DWORD
	v_sub_u16_e32 v8, v4, v8
	v_mul_u32_u24_sdwa v6, v6, s6 dst_sel:DWORD dst_unused:UNUSED_PAD src0_sel:BYTE_3 src1_sel:DWORD
	v_lshlrev_b32_e32 v7, 2, v8
	v_add3_u32 v6, s7, v6, v7
	v_mul_f32_e32 v5, 0x3fb8aa3b, v14
	ds_write_b32 v6, v5
	v_add_u32_e32 v4, 0xa00, v0
	v_mul_u32_u24_sdwa v6, v4, s4 dst_sel:DWORD dst_unused:UNUSED_PAD src0_sel:WORD_0 src1_sel:DWORD
	v_mul_lo_u16_sdwa v8, v6, s5 dst_sel:DWORD dst_unused:UNUSED_PAD src0_sel:BYTE_3 src1_sel:DWORD
	v_sub_u16_e32 v8, v4, v8
	v_mul_u32_u24_sdwa v6, v6, s6 dst_sel:DWORD dst_unused:UNUSED_PAD src0_sel:BYTE_3 src1_sel:DWORD
	v_lshlrev_b32_e32 v7, 2, v8
	v_add3_u32 v6, s7, v6, v7
	v_mul_f32_e32 v5, 0x3fb8aa3b, v15
	ds_write_b32 v6, v5
	v_add_u32_e32 v4, 0xc00, v0
	v_mul_u32_u24_sdwa v6, v4, s4 dst_sel:DWORD dst_unused:UNUSED_PAD src0_sel:WORD_0 src1_sel:DWORD
	v_mul_lo_u16_sdwa v8, v6, s5 dst_sel:DWORD dst_unused:UNUSED_PAD src0_sel:BYTE_3 src1_sel:DWORD
	v_sub_u16_e32 v8, v4, v8
	v_mul_u32_u24_sdwa v6, v6, s6 dst_sel:DWORD dst_unused:UNUSED_PAD src0_sel:BYTE_3 src1_sel:DWORD
	v_lshlrev_b32_e32 v7, 2, v8
	v_add3_u32 v6, s7, v6, v7
	v_mul_f32_e32 v5, 0x3fb8aa3b, v16
	ds_write_b32 v6, v5
	v_add_u32_e32 v4, 0xe00, v0
	v_mul_u32_u24_sdwa v6, v4, s4 dst_sel:DWORD dst_unused:UNUSED_PAD src0_sel:WORD_0 src1_sel:DWORD
	v_mul_lo_u16_sdwa v8, v6, s5 dst_sel:DWORD dst_unused:UNUSED_PAD src0_sel:BYTE_3 src1_sel:DWORD
	v_sub_u16_e32 v8, v4, v8
	v_mul_u32_u24_sdwa v6, v6, s6 dst_sel:DWORD dst_unused:UNUSED_PAD src0_sel:BYTE_3 src1_sel:DWORD
	v_lshlrev_b32_e32 v7, 2, v8
	v_add3_u32 v6, s7, v6, v7
	v_mul_f32_e32 v5, 0x3fb8aa3b, v17
	ds_write_b32 v6, v5
	s_and_saveexec_b64 s[0:1], vcc
	v_add_u32_e32 v4, 0x1000, v0
	v_mul_u32_u24_sdwa v6, v4, s4 dst_sel:DWORD dst_unused:UNUSED_PAD src0_sel:WORD_0 src1_sel:DWORD
	v_mul_lo_u16_sdwa v8, v6, s5 dst_sel:DWORD dst_unused:UNUSED_PAD src0_sel:BYTE_3 src1_sel:DWORD
	v_sub_u16_e32 v8, v4, v8
	v_mul_u32_u24_sdwa v6, v6, s6 dst_sel:DWORD dst_unused:UNUSED_PAD src0_sel:BYTE_3 src1_sel:DWORD
	v_lshlrev_b32_e32 v7, 2, v8
	v_add3_u32 v6, s7, v6, v7
	v_mul_f32_e32 v5, 0x3fb8aa3b, v18
	ds_write_b32 v6, v5
	s_mov_b64 exec, s[0:1]
	s_or_b64 exec, exec, s[0:1]
	s_add_u32 s6, s76, 0x1bc00000
	s_addc_u32 s7, s77, 0
	s_add_u32 s4, s76, 0x1de00000
	s_addc_u32 s5, s77, 0
	s_add_u32 s16, s76, 0x2c800000
	v_readlane_b32 s0, v254, 10
	s_addc_u32 s17, s77, 0
	v_readlane_b32 s2, v254, 12
	v_readlane_b32 s1, v254, 11
	s_bitcmp1_b32 s2, 2
	v_readlane_b32 s3, v254, 13
	s_cselect_b64 s[0:1], -1, 0
	s_cmpk_lt_i32 s97, 0x200
	s_cselect_b64 s[2:3], -1, 0
	s_and_b64 s[0:1], s[2:3], s[0:1]
	s_and_b64 vcc, exec, s[0:1]
	v_lshlrev_b32_e32 v175, 1, v0
	v_and_b32_e32 v174, 3, v0
	v_readlane_b32 s69, v254, 55
	s_waitcnt lgkmcnt(0)
	s_barrier
	s_cbranch_vccz .LBB0_1172
	s_add_u32 s18, s76, 0x22000000
	v_readlane_b32 s0, v254, 51
	s_addc_u32 s19, s77, 0
	s_lshr_b32 s24, s0, 7
	s_lshl_b32 s0, s60, 5
	s_and_b32 s25, s0, 32
	s_lshl_b32 s0, s60, 2
	v_and_b32_e32 v3, 15, v0
	v_lshrrev_b32_e32 v5, 4, v1
	s_and_b32 s0, s0, 12
	v_bitop3_b32 v7, s0, v3, v5 bitop3:0x36
	v_lshlrev_b32_e32 v7, 3, v7
	s_lshl_b32 s0, s60, 10
	v_lshlrev_b32_e32 v8, 7, v5
	v_or3_b32 v158, v7, v8, s0
	v_and_or_b32 v7, v175, 24, v174
	v_lshlrev_b32_e32 v176, 8, v7
	v_bitop3_b32 v7, v5, v0, 15 bitop3:0x78
	v_lshlrev_b32_e32 v179, 4, v7
	v_bitop3_b32 v7, v5, v3, 4 bitop3:0x36
	v_lshlrev_b32_e32 v180, 4, v7
	v_bitop3_b32 v7, v5, v3, 8 bitop3:0x36
	v_lshlrev_b32_e32 v6, 3, v5
	v_mov_b32_e32 v2, 0
	v_lshl_or_b32 v160, v1, 3, s0
	s_lshl_b32 s0, s60, 11
	v_lshlrev_b32_e32 v181, 4, v7
	v_bitop3_b32 v7, v5, v3, 12 bitop3:0x36
	v_lshl_or_b32 v4, v3, 7, v6
	v_mov_b32_e32 v161, v2
	s_add_i32 s26, s0, 0
	v_mov_b32_e32 v159, v2
	v_lshlrev_b32_e32 v182, 4, v7
	v_lshlrev_b32_e32 v7, 12, v3
	s_lshl_b32 s0, s24, 6
	v_lshlrev_b32_e32 v177, 6, v3
	v_and_b32_e32 v178, 48, v0
	v_lshl_or_b32 v162, v5, 2, v7
	v_mov_b32_e32 v163, v2
	v_sub_u32_e32 v183, v3, v6
	s_or_b32 s27, s0, s25
	v_lshlrev_b32_e32 v164, 1, v4
	v_mov_b32_e32 v165, v2
	s_movk_i32 s28, 0x1000
	v_lshlrev_b64 v[166:167], 1, v[160:161]
	v_lshlrev_b64 v[168:169], 1, v[158:159]
	s_mov_b64 s[8:9], 0x400
	s_add_i32 s29, s26, 0x400
	s_add_i32 s30, s26, 0x4000
	s_add_i32 s31, s26, 0x4400
	s_add_i32 s33, s26, 0x8000
	s_add_i32 s34, s26, 0x8400
	s_add_i32 s35, s26, 0xc000
	s_add_i32 s37, s26, 0xc400
	s_movk_i32 s38, 0xff80
	s_mov_b32 s0, 0x3f803f80
	s_mov_b32 s39, 0xc3e00000
	s_mov_b32 s40, 0x10000
	v_mov_b32_e32 v184, 0x80
	v_mov_b32_e32 v185, 0x43e00000
	s_mov_b32 s41, s97
	s_branch .LBB0_1155
